# TQ GEMM K-loops: two of the six LDS-DMA stage loads of the second load segment issued inside the following 16-MFMA compute segment (vmcnt 7->5)
# speedup vs baseline: 1.0015x; 1.0015x over previous
.LBB0_629:
	v_add_u32_e32 v110, s29, v159
	v_add_u32_e32 v126, s34, v159
	ds_read_b128 v[98:101], v110
	ds_read_b128 v[102:105], v110 offset:1024
	ds_read_b128 v[106:109], v110 offset:2048
	ds_read_b128 v[110:113], v110 offset:3072
	ds_read_b128 v[114:117], v126
	ds_read_b128 v[118:121], v126 offset:1024
	ds_read_b128 v[122:125], v126 offset:2048
	ds_read_b128 v[126:129], v126 offset:3072
	s_add_u32 s8, s10, 0x100
	s_addc_u32 s9, s11, 0
	s_cmpk_eq_i32 s67, 0x54
	s_cselect_b32 s71, s21, s9
	s_cselect_b32 s70, s20, s8
	s_cselect_b32 s25, s23, s66
	s_cselect_b32 s24, s22, s0
	v_lshl_add_u64 v[172:173], s[10:11], 0, v[132:133]
	s_add_i32 m0, s37, 0xc000
	ds_read_b128 v[134:137], v162
	ds_read_b128 v[138:141], v162 offset:1024
	ds_read_b128 v[142:145], v162 offset:2048
	ds_read_b128 v[146:149], v162 offset:3072
	ds_read_b128 v[150:153], v162 offset:4096
	ds_read_b128 v[154:157], v162 offset:5120
	ds_read_b128 v[164:167], v162 offset:6144
	ds_read_b128 v[168:171], v162 offset:7168
	global_load_lds_dwordx4 v[172:173], off
	s_waitcnt vmcnt(7)
	s_waitcnt lgkmcnt(0)
	s_barrier
	s_setprio 1
	s_waitcnt lgkmcnt(0)
	v_mfma_f32_16x16x32_bf16 v[94:97], v[98:101], v[134:137], v[94:97]
	v_mfma_f32_16x16x32_bf16 v[90:93], v[106:109], v[134:137], v[90:93]
	v_mfma_f32_16x16x32_bf16 v[78:81], v[98:101], v[142:145], v[78:81]
	v_mfma_f32_16x16x32_bf16 v[74:77], v[106:109], v[142:145], v[74:77]
	v_mfma_f32_16x16x32_bf16 v[62:65], v[98:101], v[150:153], v[62:65]
	v_mfma_f32_16x16x32_bf16 v[58:61], v[106:109], v[150:153], v[58:61]
	v_mfma_f32_16x16x32_bf16 v[46:49], v[98:101], v[164:167], v[46:49]
	v_mfma_f32_16x16x32_bf16 v[42:45], v[106:109], v[164:167], v[42:45]
	v_mfma_f32_16x16x32_bf16 v[94:97], v[102:105], v[138:141], v[94:97]
	v_mfma_f32_16x16x32_bf16 v[90:93], v[110:113], v[138:141], v[90:93]
	v_mfma_f32_16x16x32_bf16 v[78:81], v[102:105], v[146:149], v[78:81]
	v_mfma_f32_16x16x32_bf16 v[74:77], v[110:113], v[146:149], v[74:77]
	v_mfma_f32_16x16x32_bf16 v[62:65], v[102:105], v[154:157], v[62:65]
	v_mfma_f32_16x16x32_bf16 v[58:61], v[110:113], v[154:157], v[58:61]
	v_mfma_f32_16x16x32_bf16 v[46:49], v[102:105], v[168:171], v[46:49]
	v_mfma_f32_16x16x32_bf16 v[42:45], v[110:113], v[168:171], v[42:45]
	s_setprio 0
	s_setprio 1
	v_mfma_f32_16x16x32_bf16 v[86:89], v[114:117], v[134:137], v[86:89]
	v_mfma_f32_16x16x32_bf16 v[82:85], v[122:125], v[134:137], v[82:85]
	v_mfma_f32_16x16x32_bf16 v[70:73], v[114:117], v[142:145], v[70:73]
	v_mfma_f32_16x16x32_bf16 v[66:69], v[122:125], v[142:145], v[66:69]
	v_mfma_f32_16x16x32_bf16 v[54:57], v[114:117], v[150:153], v[54:57]
	v_mfma_f32_16x16x32_bf16 v[50:53], v[122:125], v[150:153], v[50:53]
	v_mfma_f32_16x16x32_bf16 v[38:41], v[114:117], v[164:167], v[38:41]
	v_mfma_f32_16x16x32_bf16 v[34:37], v[122:125], v[164:167], v[34:37]
	v_mfma_f32_16x16x32_bf16 v[86:89], v[118:121], v[138:141], v[86:89]
	v_mfma_f32_16x16x32_bf16 v[82:85], v[126:129], v[138:141], v[82:85]
	v_mfma_f32_16x16x32_bf16 v[70:73], v[118:121], v[146:149], v[70:73]
	v_mfma_f32_16x16x32_bf16 v[66:69], v[126:129], v[146:149], v[66:69]
	v_mfma_f32_16x16x32_bf16 v[54:57], v[118:121], v[154:157], v[54:57]
	v_mfma_f32_16x16x32_bf16 v[50:53], v[126:129], v[154:157], v[50:53]
	v_mfma_f32_16x16x32_bf16 v[38:41], v[118:121], v[168:171], v[38:41]
	v_mfma_f32_16x16x32_bf16 v[34:37], v[126:129], v[168:171], v[34:37]
	s_setprio 0
	s_barrier
	s_mov_b32 m0, s30
	v_lshl_add_u64 v[172:173], s[24:25], 0, v[0:1]
	s_add_u32 s10, s24, 0x160000
	ds_read_b128 v[134:137], v163 offset:16384
	ds_read_b128 v[138:141], v163 offset:17408
	ds_read_b128 v[142:145], v163 offset:18432
	ds_read_b128 v[146:149], v163 offset:19456
	global_load_lds_dwordx4 v[172:173], off
	v_lshl_add_u64 v[174:175], s[24:25], 0, v[130:131]
	s_mov_b32 m0, s31
	s_addc_u32 s11, s25, 0
	global_load_lds_dwordx4 v[174:175], off
	v_lshl_add_u64 v[150:151], s[10:11], 0, v[0:1]
	s_mov_b32 m0, s35
	v_lshl_add_u64 v[176:177], s[70:71], 0, v[0:1]
	global_load_lds_dwordx4 v[150:151], off
	v_lshl_add_u64 v[150:151], s[10:11], 0, v[130:131]
	s_mov_b32 m0, s36
	v_lshl_add_u64 v[178:179], s[70:71], 0, v[130:131]
	global_load_lds_dwordx4 v[150:151], off
	s_waitcnt vmcnt(5)
	s_waitcnt lgkmcnt(0)
	s_barrier
	s_setprio 1
	s_waitcnt lgkmcnt(0)
	v_mfma_f32_16x16x32_bf16 v[30:33], v[98:101], v[134:137], v[30:33]
	v_mfma_f32_16x16x32_bf16 v[26:29], v[106:109], v[134:137], v[26:29]
	v_mfma_f32_16x16x32_bf16 v[14:17], v[98:101], v[142:145], v[14:17]
	s_mov_b32 m0, s37
	s_nop 0
	global_load_lds_dwordx4 v[176:177], off
	v_mfma_f32_16x16x32_bf16 v[10:13], v[106:109], v[142:145], v[10:13]
	v_mfma_f32_16x16x32_bf16 v[30:33], v[102:105], v[138:141], v[30:33]
	v_mfma_f32_16x16x32_bf16 v[26:29], v[110:113], v[138:141], v[26:29]
	v_mfma_f32_16x16x32_bf16 v[14:17], v[102:105], v[146:149], v[14:17]
	v_mfma_f32_16x16x32_bf16 v[10:13], v[110:113], v[146:149], v[10:13]
	s_setprio 0
	s_setprio 1
	v_mfma_f32_16x16x32_bf16 v[22:25], v[114:117], v[134:137], v[22:25]
	v_mfma_f32_16x16x32_bf16 v[18:21], v[122:125], v[134:137], v[18:21]
	v_mfma_f32_16x16x32_bf16 v[6:9], v[114:117], v[142:145], v[6:9]
	s_mov_b32 m0, s38
	s_nop 0
	global_load_lds_dwordx4 v[178:179], off
	v_mfma_f32_16x16x32_bf16 v[2:5], v[122:125], v[142:145], v[2:5]
	v_mfma_f32_16x16x32_bf16 v[22:25], v[118:121], v[138:141], v[22:25]
	v_mfma_f32_16x16x32_bf16 v[18:21], v[126:129], v[138:141], v[18:21]
	v_mfma_f32_16x16x32_bf16 v[6:9], v[118:121], v[146:149], v[6:9]
	v_mfma_f32_16x16x32_bf16 v[2:5], v[126:129], v[146:149], v[2:5]
	s_setprio 0
	s_barrier
	v_add_u32_e32 v110, s43, v159
	v_add_u32_e32 v126, s53, v159
	ds_read_b128 v[98:101], v110
	ds_read_b128 v[102:105], v110 offset:1024
	ds_read_b128 v[106:109], v110 offset:2048
	ds_read_b128 v[110:113], v110 offset:3072
	ds_read_b128 v[114:117], v126
	ds_read_b128 v[118:121], v126 offset:1024
	ds_read_b128 v[122:125], v126 offset:2048
	ds_read_b128 v[126:129], v126 offset:3072
	v_lshl_add_u64 v[180:181], v[176:177], 0, s[82:83]
	s_mov_b32 m0, s39
	ds_read_b128 v[134:137], v162 offset:32768
	ds_read_b128 v[138:141], v162 offset:33792
	ds_read_b128 v[142:145], v162 offset:34816
	ds_read_b128 v[146:149], v162 offset:35840
	ds_read_b128 v[150:153], v162 offset:36864
	ds_read_b128 v[154:157], v162 offset:37888
	ds_read_b128 v[164:167], v162 offset:38912
	ds_read_b128 v[168:171], v162 offset:39936
	global_load_lds_dwordx4 v[180:181], off
	s_waitcnt vmcnt(7)
	s_waitcnt lgkmcnt(0)
	s_barrier
	s_setprio 1
	s_waitcnt lgkmcnt(0)
	v_mfma_f32_16x16x32_bf16 v[94:97], v[98:101], v[134:137], v[94:97]
	v_mfma_f32_16x16x32_bf16 v[90:93], v[106:109], v[134:137], v[90:93]
	v_mfma_f32_16x16x32_bf16 v[78:81], v[98:101], v[142:145], v[78:81]
	v_mfma_f32_16x16x32_bf16 v[74:77], v[106:109], v[142:145], v[74:77]
	v_mfma_f32_16x16x32_bf16 v[62:65], v[98:101], v[150:153], v[62:65]
	v_mfma_f32_16x16x32_bf16 v[58:61], v[106:109], v[150:153], v[58:61]
	v_mfma_f32_16x16x32_bf16 v[46:49], v[98:101], v[164:167], v[46:49]
	v_mfma_f32_16x16x32_bf16 v[42:45], v[106:109], v[164:167], v[42:45]
	v_mfma_f32_16x16x32_bf16 v[94:97], v[102:105], v[138:141], v[94:97]
	v_mfma_f32_16x16x32_bf16 v[90:93], v[110:113], v[138:141], v[90:93]
	v_mfma_f32_16x16x32_bf16 v[78:81], v[102:105], v[146:149], v[78:81]
	v_mfma_f32_16x16x32_bf16 v[74:77], v[110:113], v[146:149], v[74:77]
	v_mfma_f32_16x16x32_bf16 v[62:65], v[102:105], v[154:157], v[62:65]
	v_mfma_f32_16x16x32_bf16 v[58:61], v[110:113], v[154:157], v[58:61]
	v_mfma_f32_16x16x32_bf16 v[46:49], v[102:105], v[168:171], v[46:49]
	v_mfma_f32_16x16x32_bf16 v[42:45], v[110:113], v[168:171], v[42:45]
	s_setprio 0
	s_setprio 1
	v_mfma_f32_16x16x32_bf16 v[86:89], v[114:117], v[134:137], v[86:89]
	v_mfma_f32_16x16x32_bf16 v[82:85], v[122:125], v[134:137], v[82:85]
	v_mfma_f32_16x16x32_bf16 v[70:73], v[114:117], v[142:145], v[70:73]
	v_mfma_f32_16x16x32_bf16 v[66:69], v[122:125], v[142:145], v[66:69]
	v_mfma_f32_16x16x32_bf16 v[54:57], v[114:117], v[150:153], v[54:57]
	v_mfma_f32_16x16x32_bf16 v[50:53], v[122:125], v[150:153], v[50:53]
	v_mfma_f32_16x16x32_bf16 v[38:41], v[114:117], v[164:167], v[38:41]
	v_mfma_f32_16x16x32_bf16 v[34:37], v[122:125], v[164:167], v[34:37]
	v_mfma_f32_16x16x32_bf16 v[86:89], v[118:121], v[138:141], v[86:89]
	v_mfma_f32_16x16x32_bf16 v[82:85], v[126:129], v[138:141], v[82:85]
	v_mfma_f32_16x16x32_bf16 v[70:73], v[118:121], v[146:149], v[70:73]
	v_mfma_f32_16x16x32_bf16 v[66:69], v[126:129], v[146:149], v[66:69]
	v_mfma_f32_16x16x32_bf16 v[54:57], v[118:121], v[154:157], v[54:57]
	v_mfma_f32_16x16x32_bf16 v[50:53], v[126:129], v[154:157], v[50:53]
	v_mfma_f32_16x16x32_bf16 v[38:41], v[118:121], v[168:171], v[38:41]
	v_mfma_f32_16x16x32_bf16 v[34:37], v[126:129], v[168:171], v[34:37]
	s_setprio 0
	s_barrier
	s_mov_b32 m0, s49
	v_lshl_add_u64 v[150:151], v[172:173], 0, s[44:45]
	s_add_u32 s10, s24, 0x160080
	ds_read_b128 v[134:137], v163 offset:49152
	ds_read_b128 v[138:141], v163 offset:50176
	ds_read_b128 v[142:145], v163 offset:51200
	ds_read_b128 v[146:149], v163 offset:52224
	global_load_lds_dwordx4 v[150:151], off
	v_lshl_add_u64 v[150:151], v[174:175], 0, s[44:45]
	s_mov_b32 m0, s50
	s_addc_u32 s11, s25, 0
	global_load_lds_dwordx4 v[150:151], off
	v_lshl_add_u64 v[150:151], s[10:11], 0, v[0:1]
	s_mov_b32 m0, s54
	s_nop 0
	global_load_lds_dwordx4 v[150:151], off
	v_lshl_add_u64 v[150:151], s[10:11], 0, v[130:131]
	s_mov_b32 m0, s55
	s_nop 0
	global_load_lds_dwordx4 v[150:151], off
	s_waitcnt vmcnt(5)
	s_waitcnt lgkmcnt(0)
	s_barrier
	s_setprio 1
	s_waitcnt lgkmcnt(0)
	v_mfma_f32_16x16x32_bf16 v[30:33], v[98:101], v[134:137], v[30:33]
	v_mfma_f32_16x16x32_bf16 v[26:29], v[106:109], v[134:137], v[26:29]
	v_mfma_f32_16x16x32_bf16 v[14:17], v[98:101], v[142:145], v[14:17]
	v_lshl_add_u64 v[150:151], v[176:177], 0, s[44:45]
	s_mov_b32 m0, s51
	s_nop 0
	global_load_lds_dwordx4 v[150:151], off
	v_mfma_f32_16x16x32_bf16 v[10:13], v[106:109], v[142:145], v[10:13]
	v_mfma_f32_16x16x32_bf16 v[30:33], v[102:105], v[138:141], v[30:33]
	v_mfma_f32_16x16x32_bf16 v[26:29], v[110:113], v[138:141], v[26:29]
	v_mfma_f32_16x16x32_bf16 v[14:17], v[102:105], v[146:149], v[14:17]
	v_mfma_f32_16x16x32_bf16 v[10:13], v[110:113], v[146:149], v[10:13]
	s_setprio 0
	s_setprio 1
	v_mfma_f32_16x16x32_bf16 v[22:25], v[114:117], v[134:137], v[22:25]
	v_mfma_f32_16x16x32_bf16 v[18:21], v[122:125], v[134:137], v[18:21]
	v_mfma_f32_16x16x32_bf16 v[6:9], v[114:117], v[142:145], v[6:9]
	v_lshl_add_u64 v[150:151], v[178:179], 0, s[44:45]
	s_mov_b32 m0, s52
	s_nop 0
	global_load_lds_dwordx4 v[150:151], off
	v_mfma_f32_16x16x32_bf16 v[2:5], v[122:125], v[142:145], v[2:5]
	v_mfma_f32_16x16x32_bf16 v[22:25], v[118:121], v[138:141], v[22:25]
	v_mfma_f32_16x16x32_bf16 v[18:21], v[126:129], v[138:141], v[18:21]
	v_mfma_f32_16x16x32_bf16 v[6:9], v[118:121], v[146:149], v[6:9]
	v_mfma_f32_16x16x32_bf16 v[2:5], v[126:129], v[146:149], v[2:5]
	s_setprio 0
	s_barrier
	s_add_i32 s67, s67, 2
	s_add_u32 s0, s0, 0x100
	s_addc_u32 s66, s66, 0
	s_cmpk_gt_u32 s67, 0x55
	s_mov_b64 s[10:11], s[8:9]
	s_cbranch_scc0 .LBB0_629
	s_and_b64 vcc, exec, s[18:19]
	s_cbranch_vccz .LBB0_632
	s_barrier

.LBB0_1468:
	v_add_u32_e32 v110, s27, v159
	v_add_u32_e32 v126, s30, v159
	ds_read_b128 v[98:101], v110
	ds_read_b128 v[102:105], v110 offset:1024
	ds_read_b128 v[106:109], v110 offset:2048
	ds_read_b128 v[110:113], v110 offset:3072
	ds_read_b128 v[114:117], v126
	ds_read_b128 v[118:121], v126 offset:1024
	ds_read_b128 v[122:125], v126 offset:2048
	ds_read_b128 v[126:129], v126 offset:3072
	s_add_u32 s8, s10, 0x100
	s_addc_u32 s9, s11, 0
	s_cmp_eq_u32 s67, 28
	s_cselect_b32 s71, s19, s9
	s_cselect_b32 s70, s18, s8
	s_cselect_b32 s23, s0, s66
	s_cselect_b32 s22, s17, s61
	v_lshl_add_u64 v[172:173], s[10:11], 0, v[148:149]
	s_add_i32 m0, s35, 0xc000
	ds_read_b128 v[130:133], v162
	ds_read_b128 v[134:137], v162 offset:1024
	ds_read_b128 v[138:141], v162 offset:2048
	ds_read_b128 v[142:145], v162 offset:3072
	ds_read_b128 v[150:153], v162 offset:4096
	ds_read_b128 v[154:157], v162 offset:5120
	ds_read_b128 v[164:167], v162 offset:6144
	ds_read_b128 v[168:171], v162 offset:7168
	global_load_lds_dwordx4 v[172:173], off
	s_waitcnt vmcnt(7)
	s_waitcnt lgkmcnt(0)
	s_barrier
	s_setprio 1
	s_waitcnt lgkmcnt(0)
	v_mfma_f32_16x16x32_bf16 v[94:97], v[98:101], v[130:133], v[94:97]
	v_mfma_f32_16x16x32_bf16 v[90:93], v[106:109], v[130:133], v[90:93]
	v_mfma_f32_16x16x32_bf16 v[78:81], v[98:101], v[138:141], v[78:81]
	v_mfma_f32_16x16x32_bf16 v[74:77], v[106:109], v[138:141], v[74:77]
	v_mfma_f32_16x16x32_bf16 v[62:65], v[98:101], v[150:153], v[62:65]
	v_mfma_f32_16x16x32_bf16 v[58:61], v[106:109], v[150:153], v[58:61]
	v_mfma_f32_16x16x32_bf16 v[46:49], v[98:101], v[164:167], v[46:49]
	v_mfma_f32_16x16x32_bf16 v[42:45], v[106:109], v[164:167], v[42:45]
	v_mfma_f32_16x16x32_bf16 v[94:97], v[102:105], v[134:137], v[94:97]
	v_mfma_f32_16x16x32_bf16 v[90:93], v[110:113], v[134:137], v[90:93]
	v_mfma_f32_16x16x32_bf16 v[78:81], v[102:105], v[142:145], v[78:81]
	v_mfma_f32_16x16x32_bf16 v[74:77], v[110:113], v[142:145], v[74:77]
	v_mfma_f32_16x16x32_bf16 v[62:65], v[102:105], v[154:157], v[62:65]
	v_mfma_f32_16x16x32_bf16 v[58:61], v[110:113], v[154:157], v[58:61]
	v_mfma_f32_16x16x32_bf16 v[46:49], v[102:105], v[168:171], v[46:49]
	v_mfma_f32_16x16x32_bf16 v[42:45], v[110:113], v[168:171], v[42:45]
	s_setprio 0
	s_setprio 1
	v_mfma_f32_16x16x32_bf16 v[86:89], v[114:117], v[130:133], v[86:89]
	v_mfma_f32_16x16x32_bf16 v[82:85], v[122:125], v[130:133], v[82:85]
	v_mfma_f32_16x16x32_bf16 v[70:73], v[114:117], v[138:141], v[70:73]
	v_mfma_f32_16x16x32_bf16 v[66:69], v[122:125], v[138:141], v[66:69]
	v_mfma_f32_16x16x32_bf16 v[54:57], v[114:117], v[150:153], v[54:57]
	v_mfma_f32_16x16x32_bf16 v[50:53], v[122:125], v[150:153], v[50:53]
	v_mfma_f32_16x16x32_bf16 v[38:41], v[114:117], v[164:167], v[38:41]
	v_mfma_f32_16x16x32_bf16 v[34:37], v[122:125], v[164:167], v[34:37]
	v_mfma_f32_16x16x32_bf16 v[86:89], v[118:121], v[134:137], v[86:89]
	v_mfma_f32_16x16x32_bf16 v[82:85], v[126:129], v[134:137], v[82:85]
	v_mfma_f32_16x16x32_bf16 v[70:73], v[118:121], v[142:145], v[70:73]
	v_mfma_f32_16x16x32_bf16 v[66:69], v[126:129], v[142:145], v[66:69]
	v_mfma_f32_16x16x32_bf16 v[54:57], v[118:121], v[154:157], v[54:57]
	v_mfma_f32_16x16x32_bf16 v[50:53], v[126:129], v[154:157], v[50:53]
	v_mfma_f32_16x16x32_bf16 v[38:41], v[118:121], v[168:171], v[38:41]
	v_mfma_f32_16x16x32_bf16 v[34:37], v[126:129], v[168:171], v[34:37]
	s_setprio 0
	s_barrier
	s_mov_b32 m0, s28
	v_lshl_add_u64 v[172:173], s[22:23], 0, v[0:1]
	s_add_u32 s10, s22, 0x80000
	ds_read_b128 v[130:133], v163 offset:16384
	ds_read_b128 v[134:137], v163 offset:17408
	ds_read_b128 v[138:141], v163 offset:18432
	ds_read_b128 v[142:145], v163 offset:19456
	global_load_lds_dwordx4 v[172:173], off
	v_lshl_add_u64 v[174:175], s[22:23], 0, v[146:147]
	s_mov_b32 m0, s29
	s_addc_u32 s11, s23, 0
	global_load_lds_dwordx4 v[174:175], off
	v_lshl_add_u64 v[150:151], s[10:11], 0, v[0:1]
	s_mov_b32 m0, s31
	v_lshl_add_u64 v[176:177], s[70:71], 0, v[0:1]
	global_load_lds_dwordx4 v[150:151], off
	v_lshl_add_u64 v[150:151], s[10:11], 0, v[146:147]
	s_mov_b32 m0, s34
	v_lshl_add_u64 v[178:179], s[70:71], 0, v[146:147]
	global_load_lds_dwordx4 v[150:151], off
	s_waitcnt vmcnt(5)
	s_waitcnt lgkmcnt(0)
	s_barrier
	s_setprio 1
	s_waitcnt lgkmcnt(0)
	v_mfma_f32_16x16x32_bf16 v[30:33], v[98:101], v[130:133], v[30:33]
	v_mfma_f32_16x16x32_bf16 v[26:29], v[106:109], v[130:133], v[26:29]
	v_mfma_f32_16x16x32_bf16 v[14:17], v[98:101], v[138:141], v[14:17]
	s_mov_b32 m0, s35
	s_nop 0
	global_load_lds_dwordx4 v[176:177], off
	v_mfma_f32_16x16x32_bf16 v[10:13], v[106:109], v[138:141], v[10:13]
	v_mfma_f32_16x16x32_bf16 v[30:33], v[102:105], v[134:137], v[30:33]
	v_mfma_f32_16x16x32_bf16 v[26:29], v[110:113], v[134:137], v[26:29]
	v_mfma_f32_16x16x32_bf16 v[14:17], v[102:105], v[142:145], v[14:17]
	v_mfma_f32_16x16x32_bf16 v[10:13], v[110:113], v[142:145], v[10:13]
	s_setprio 0
	s_setprio 1
	v_mfma_f32_16x16x32_bf16 v[22:25], v[114:117], v[130:133], v[22:25]
	v_mfma_f32_16x16x32_bf16 v[18:21], v[122:125], v[130:133], v[18:21]
	v_mfma_f32_16x16x32_bf16 v[6:9], v[114:117], v[138:141], v[6:9]
	s_mov_b32 m0, s36
	s_nop 0
	global_load_lds_dwordx4 v[178:179], off
	v_mfma_f32_16x16x32_bf16 v[2:5], v[122:125], v[138:141], v[2:5]
	v_mfma_f32_16x16x32_bf16 v[22:25], v[118:121], v[134:137], v[22:25]
	v_mfma_f32_16x16x32_bf16 v[18:21], v[126:129], v[134:137], v[18:21]
	v_mfma_f32_16x16x32_bf16 v[6:9], v[118:121], v[142:145], v[6:9]
	v_mfma_f32_16x16x32_bf16 v[2:5], v[126:129], v[142:145], v[2:5]
	s_setprio 0
	s_barrier
	v_add_u32_e32 v110, s43, v159
	v_add_u32_e32 v126, s53, v159
	ds_read_b128 v[98:101], v110
	ds_read_b128 v[102:105], v110 offset:1024
	ds_read_b128 v[106:109], v110 offset:2048
	ds_read_b128 v[110:113], v110 offset:3072
	ds_read_b128 v[114:117], v126
	ds_read_b128 v[118:121], v126 offset:1024
	ds_read_b128 v[122:125], v126 offset:2048
	ds_read_b128 v[126:129], v126 offset:3072
	v_lshl_add_u64 v[180:181], v[176:177], 0, s[62:63]
	s_mov_b32 m0, s37
	ds_read_b128 v[130:133], v162 offset:32768
	ds_read_b128 v[134:137], v162 offset:33792
	ds_read_b128 v[138:141], v162 offset:34816
	ds_read_b128 v[142:145], v162 offset:35840
	ds_read_b128 v[150:153], v162 offset:36864
	ds_read_b128 v[154:157], v162 offset:37888
	ds_read_b128 v[164:167], v162 offset:38912
	ds_read_b128 v[168:171], v162 offset:39936
	global_load_lds_dwordx4 v[180:181], off
	s_waitcnt vmcnt(7)
	s_waitcnt lgkmcnt(0)
	s_barrier
	s_setprio 1
	s_waitcnt lgkmcnt(0)
	v_mfma_f32_16x16x32_bf16 v[94:97], v[98:101], v[130:133], v[94:97]
	v_mfma_f32_16x16x32_bf16 v[90:93], v[106:109], v[130:133], v[90:93]
	v_mfma_f32_16x16x32_bf16 v[78:81], v[98:101], v[138:141], v[78:81]
	v_mfma_f32_16x16x32_bf16 v[74:77], v[106:109], v[138:141], v[74:77]
	v_mfma_f32_16x16x32_bf16 v[62:65], v[98:101], v[150:153], v[62:65]
	v_mfma_f32_16x16x32_bf16 v[58:61], v[106:109], v[150:153], v[58:61]
	v_mfma_f32_16x16x32_bf16 v[46:49], v[98:101], v[164:167], v[46:49]
	v_mfma_f32_16x16x32_bf16 v[42:45], v[106:109], v[164:167], v[42:45]
	v_mfma_f32_16x16x32_bf16 v[94:97], v[102:105], v[134:137], v[94:97]
	v_mfma_f32_16x16x32_bf16 v[90:93], v[110:113], v[134:137], v[90:93]
	v_mfma_f32_16x16x32_bf16 v[78:81], v[102:105], v[142:145], v[78:81]
	v_mfma_f32_16x16x32_bf16 v[74:77], v[110:113], v[142:145], v[74:77]
	v_mfma_f32_16x16x32_bf16 v[62:65], v[102:105], v[154:157], v[62:65]
	v_mfma_f32_16x16x32_bf16 v[58:61], v[110:113], v[154:157], v[58:61]
	v_mfma_f32_16x16x32_bf16 v[46:49], v[102:105], v[168:171], v[46:49]
	v_mfma_f32_16x16x32_bf16 v[42:45], v[110:113], v[168:171], v[42:45]
	s_setprio 0
	s_setprio 1
	v_mfma_f32_16x16x32_bf16 v[86:89], v[114:117], v[130:133], v[86:89]
	v_mfma_f32_16x16x32_bf16 v[82:85], v[122:125], v[130:133], v[82:85]
	v_mfma_f32_16x16x32_bf16 v[70:73], v[114:117], v[138:141], v[70:73]
	v_mfma_f32_16x16x32_bf16 v[66:69], v[122:125], v[138:141], v[66:69]
	v_mfma_f32_16x16x32_bf16 v[54:57], v[114:117], v[150:153], v[54:57]
	v_mfma_f32_16x16x32_bf16 v[50:53], v[122:125], v[150:153], v[50:53]
	v_mfma_f32_16x16x32_bf16 v[38:41], v[114:117], v[164:167], v[38:41]
	v_mfma_f32_16x16x32_bf16 v[34:37], v[122:125], v[164:167], v[34:37]
	v_mfma_f32_16x16x32_bf16 v[86:89], v[118:121], v[134:137], v[86:89]
	v_mfma_f32_16x16x32_bf16 v[82:85], v[126:129], v[134:137], v[82:85]
	v_mfma_f32_16x16x32_bf16 v[70:73], v[118:121], v[142:145], v[70:73]
	v_mfma_f32_16x16x32_bf16 v[66:69], v[126:129], v[142:145], v[66:69]
	v_mfma_f32_16x16x32_bf16 v[54:57], v[118:121], v[154:157], v[54:57]
	v_mfma_f32_16x16x32_bf16 v[50:53], v[126:129], v[154:157], v[50:53]
	v_mfma_f32_16x16x32_bf16 v[38:41], v[118:121], v[168:171], v[38:41]
	v_mfma_f32_16x16x32_bf16 v[34:37], v[126:129], v[168:171], v[34:37]
	s_setprio 0
	s_barrier
	s_mov_b32 m0, s49
	v_lshl_add_u64 v[150:151], v[172:173], 0, s[44:45]
	s_add_u32 s10, s22, 0x80080
	ds_read_b128 v[130:133], v163 offset:49152
	ds_read_b128 v[134:137], v163 offset:50176
	ds_read_b128 v[138:141], v163 offset:51200
	ds_read_b128 v[142:145], v163 offset:52224
	global_load_lds_dwordx4 v[150:151], off
	v_lshl_add_u64 v[150:151], v[174:175], 0, s[44:45]
	s_mov_b32 m0, s50
	s_addc_u32 s11, s23, 0
	global_load_lds_dwordx4 v[150:151], off
	v_lshl_add_u64 v[150:151], s[10:11], 0, v[0:1]
	s_mov_b32 m0, s54
	s_nop 0
	global_load_lds_dwordx4 v[150:151], off
	v_lshl_add_u64 v[150:151], s[10:11], 0, v[146:147]
	s_mov_b32 m0, s55
	s_nop 0
	global_load_lds_dwordx4 v[150:151], off
	s_waitcnt vmcnt(5)
	s_waitcnt lgkmcnt(0)
	s_barrier
	s_setprio 1
	s_waitcnt lgkmcnt(0)
	v_mfma_f32_16x16x32_bf16 v[30:33], v[98:101], v[130:133], v[30:33]
	v_mfma_f32_16x16x32_bf16 v[26:29], v[106:109], v[130:133], v[26:29]
	v_mfma_f32_16x16x32_bf16 v[14:17], v[98:101], v[138:141], v[14:17]
	v_lshl_add_u64 v[150:151], v[176:177], 0, s[44:45]
	s_mov_b32 m0, s51
	s_nop 0
	global_load_lds_dwordx4 v[150:151], off
	v_mfma_f32_16x16x32_bf16 v[10:13], v[106:109], v[138:141], v[10:13]
	v_mfma_f32_16x16x32_bf16 v[30:33], v[102:105], v[134:137], v[30:33]
	v_mfma_f32_16x16x32_bf16 v[26:29], v[110:113], v[134:137], v[26:29]
	v_mfma_f32_16x16x32_bf16 v[14:17], v[102:105], v[142:145], v[14:17]
	v_mfma_f32_16x16x32_bf16 v[10:13], v[110:113], v[142:145], v[10:13]
	s_setprio 0
	s_setprio 1
	v_mfma_f32_16x16x32_bf16 v[22:25], v[114:117], v[130:133], v[22:25]
	v_mfma_f32_16x16x32_bf16 v[18:21], v[122:125], v[130:133], v[18:21]
	v_mfma_f32_16x16x32_bf16 v[6:9], v[114:117], v[138:141], v[6:9]
	v_lshl_add_u64 v[150:151], v[178:179], 0, s[44:45]
	s_mov_b32 m0, s52
	s_nop 0
	global_load_lds_dwordx4 v[150:151], off
	v_mfma_f32_16x16x32_bf16 v[2:5], v[122:125], v[138:141], v[2:5]
	v_mfma_f32_16x16x32_bf16 v[22:25], v[118:121], v[134:137], v[22:25]
	v_mfma_f32_16x16x32_bf16 v[18:21], v[126:129], v[134:137], v[18:21]
	v_mfma_f32_16x16x32_bf16 v[6:9], v[118:121], v[142:145], v[6:9]
	v_mfma_f32_16x16x32_bf16 v[2:5], v[126:129], v[142:145], v[2:5]
	s_setprio 0
	s_barrier
	s_add_i32 s67, s67, 2
	s_add_u32 s61, s61, 0x100
	s_addc_u32 s66, s66, 0
	s_cmp_gt_u32 s67, 29
	s_mov_b64 s[10:11], s[8:9]
	s_cbranch_scc0 .LBB0_1468
	s_and_b64 vcc, exec, s[14:15]
	s_cbranch_vccz .LBB0_1471
	s_barrier

.LBB0_1793:
	v_add_u32_e32 v110, s25, v159
	v_add_u32_e32 v126, s28, v159
	ds_read_b128 v[98:101], v110
	ds_read_b128 v[102:105], v110 offset:1024
	ds_read_b128 v[106:109], v110 offset:2048
	ds_read_b128 v[110:113], v110 offset:3072
	ds_read_b128 v[114:117], v126
	ds_read_b128 v[118:121], v126 offset:1024
	ds_read_b128 v[122:125], v126 offset:2048
	ds_read_b128 v[126:129], v126 offset:3072
	s_add_u32 s4, s8, 0x100
	s_addc_u32 s5, s9, 0
	s_cmpk_eq_i32 s61, 0x54
	s_cselect_b32 s67, s17, s5
	s_cselect_b32 s66, s16, s4
	s_cselect_b32 s21, s19, s60
	s_cselect_b32 s20, s18, s0
	v_lshl_add_u64 v[172:173], s[8:9], 0, v[132:133]
	s_add_i32 m0, s31, 0xc000
	ds_read_b128 v[134:137], v162
	ds_read_b128 v[138:141], v162 offset:1024
	ds_read_b128 v[142:145], v162 offset:2048
	ds_read_b128 v[146:149], v162 offset:3072
	ds_read_b128 v[150:153], v162 offset:4096
	ds_read_b128 v[154:157], v162 offset:5120
	ds_read_b128 v[164:167], v162 offset:6144
	ds_read_b128 v[168:171], v162 offset:7168
	global_load_lds_dwordx4 v[172:173], off
	s_waitcnt vmcnt(7)
	s_waitcnt lgkmcnt(0)
	s_barrier
	s_setprio 1
	s_waitcnt lgkmcnt(0)
	v_mfma_f32_16x16x32_bf16 v[94:97], v[98:101], v[134:137], v[94:97]
	v_mfma_f32_16x16x32_bf16 v[90:93], v[106:109], v[134:137], v[90:93]
	v_mfma_f32_16x16x32_bf16 v[78:81], v[98:101], v[142:145], v[78:81]
	v_mfma_f32_16x16x32_bf16 v[74:77], v[106:109], v[142:145], v[74:77]
	v_mfma_f32_16x16x32_bf16 v[62:65], v[98:101], v[150:153], v[62:65]
	v_mfma_f32_16x16x32_bf16 v[58:61], v[106:109], v[150:153], v[58:61]
	v_mfma_f32_16x16x32_bf16 v[46:49], v[98:101], v[164:167], v[46:49]
	v_mfma_f32_16x16x32_bf16 v[42:45], v[106:109], v[164:167], v[42:45]
	v_mfma_f32_16x16x32_bf16 v[94:97], v[102:105], v[138:141], v[94:97]
	v_mfma_f32_16x16x32_bf16 v[90:93], v[110:113], v[138:141], v[90:93]
	v_mfma_f32_16x16x32_bf16 v[78:81], v[102:105], v[146:149], v[78:81]
	v_mfma_f32_16x16x32_bf16 v[74:77], v[110:113], v[146:149], v[74:77]
	v_mfma_f32_16x16x32_bf16 v[62:65], v[102:105], v[154:157], v[62:65]
	v_mfma_f32_16x16x32_bf16 v[58:61], v[110:113], v[154:157], v[58:61]
	v_mfma_f32_16x16x32_bf16 v[46:49], v[102:105], v[168:171], v[46:49]
	v_mfma_f32_16x16x32_bf16 v[42:45], v[110:113], v[168:171], v[42:45]
	s_setprio 0
	s_setprio 1
	v_mfma_f32_16x16x32_bf16 v[86:89], v[114:117], v[134:137], v[86:89]
	v_mfma_f32_16x16x32_bf16 v[82:85], v[122:125], v[134:137], v[82:85]
	v_mfma_f32_16x16x32_bf16 v[70:73], v[114:117], v[142:145], v[70:73]
	v_mfma_f32_16x16x32_bf16 v[66:69], v[122:125], v[142:145], v[66:69]
	v_mfma_f32_16x16x32_bf16 v[54:57], v[114:117], v[150:153], v[54:57]
	v_mfma_f32_16x16x32_bf16 v[50:53], v[122:125], v[150:153], v[50:53]
	v_mfma_f32_16x16x32_bf16 v[38:41], v[114:117], v[164:167], v[38:41]
	v_mfma_f32_16x16x32_bf16 v[34:37], v[122:125], v[164:167], v[34:37]
	v_mfma_f32_16x16x32_bf16 v[86:89], v[118:121], v[138:141], v[86:89]
	v_mfma_f32_16x16x32_bf16 v[82:85], v[126:129], v[138:141], v[82:85]
	v_mfma_f32_16x16x32_bf16 v[70:73], v[118:121], v[146:149], v[70:73]
	v_mfma_f32_16x16x32_bf16 v[66:69], v[126:129], v[146:149], v[66:69]
	v_mfma_f32_16x16x32_bf16 v[54:57], v[118:121], v[154:157], v[54:57]
	v_mfma_f32_16x16x32_bf16 v[50:53], v[126:129], v[154:157], v[50:53]
	v_mfma_f32_16x16x32_bf16 v[38:41], v[118:121], v[168:171], v[38:41]
	v_mfma_f32_16x16x32_bf16 v[34:37], v[126:129], v[168:171], v[34:37]
	s_setprio 0
	s_barrier
	s_mov_b32 m0, s26
	v_lshl_add_u64 v[172:173], s[20:21], 0, v[0:1]
	s_add_u32 s8, s20, 0x160000
	ds_read_b128 v[134:137], v163 offset:16384
	ds_read_b128 v[138:141], v163 offset:17408
	ds_read_b128 v[142:145], v163 offset:18432
	ds_read_b128 v[146:149], v163 offset:19456
	global_load_lds_dwordx4 v[172:173], off
	v_lshl_add_u64 v[174:175], s[20:21], 0, v[130:131]
	s_mov_b32 m0, s27
	s_addc_u32 s9, s21, 0
	global_load_lds_dwordx4 v[174:175], off
	v_lshl_add_u64 v[150:151], s[8:9], 0, v[0:1]
	s_mov_b32 m0, s29
	v_lshl_add_u64 v[176:177], s[66:67], 0, v[0:1]
	global_load_lds_dwordx4 v[150:151], off
	v_lshl_add_u64 v[150:151], s[8:9], 0, v[130:131]
	s_mov_b32 m0, s30
	v_lshl_add_u64 v[178:179], s[66:67], 0, v[130:131]
	global_load_lds_dwordx4 v[150:151], off
	s_waitcnt vmcnt(5)
	s_waitcnt lgkmcnt(0)
	s_barrier
	s_setprio 1
	s_waitcnt lgkmcnt(0)
	v_mfma_f32_16x16x32_bf16 v[30:33], v[98:101], v[134:137], v[30:33]
	v_mfma_f32_16x16x32_bf16 v[26:29], v[106:109], v[134:137], v[26:29]
	v_mfma_f32_16x16x32_bf16 v[14:17], v[98:101], v[142:145], v[14:17]
	s_mov_b32 m0, s31
	s_nop 0
	global_load_lds_dwordx4 v[176:177], off
	v_mfma_f32_16x16x32_bf16 v[10:13], v[106:109], v[142:145], v[10:13]
	v_mfma_f32_16x16x32_bf16 v[30:33], v[102:105], v[138:141], v[30:33]
	v_mfma_f32_16x16x32_bf16 v[26:29], v[110:113], v[138:141], v[26:29]
	v_mfma_f32_16x16x32_bf16 v[14:17], v[102:105], v[146:149], v[14:17]
	v_mfma_f32_16x16x32_bf16 v[10:13], v[110:113], v[146:149], v[10:13]
	s_setprio 0
	s_setprio 1
	v_mfma_f32_16x16x32_bf16 v[22:25], v[114:117], v[134:137], v[22:25]
	v_mfma_f32_16x16x32_bf16 v[18:21], v[122:125], v[134:137], v[18:21]
	v_mfma_f32_16x16x32_bf16 v[6:9], v[114:117], v[142:145], v[6:9]
	s_mov_b32 m0, s34
	s_nop 0
	global_load_lds_dwordx4 v[178:179], off
	v_mfma_f32_16x16x32_bf16 v[2:5], v[122:125], v[142:145], v[2:5]
	v_mfma_f32_16x16x32_bf16 v[22:25], v[118:121], v[138:141], v[22:25]
	v_mfma_f32_16x16x32_bf16 v[18:21], v[126:129], v[138:141], v[18:21]
	v_mfma_f32_16x16x32_bf16 v[6:9], v[118:121], v[146:149], v[6:9]
	v_mfma_f32_16x16x32_bf16 v[2:5], v[126:129], v[146:149], v[2:5]
	s_setprio 0
	s_barrier
	v_add_u32_e32 v110, s41, v159
	v_add_u32_e32 v126, s51, v159
	ds_read_b128 v[98:101], v110
	ds_read_b128 v[102:105], v110 offset:1024
	ds_read_b128 v[106:109], v110 offset:2048
	ds_read_b128 v[110:113], v110 offset:3072
	ds_read_b128 v[114:117], v126
	ds_read_b128 v[118:121], v126 offset:1024
	ds_read_b128 v[122:125], v126 offset:2048
	ds_read_b128 v[126:129], v126 offset:3072
	v_lshl_add_u64 v[180:181], v[176:177], 0, s[82:83]
	s_mov_b32 m0, s35
	ds_read_b128 v[134:137], v162 offset:32768
	ds_read_b128 v[138:141], v162 offset:33792
	ds_read_b128 v[142:145], v162 offset:34816
	ds_read_b128 v[146:149], v162 offset:35840
	ds_read_b128 v[150:153], v162 offset:36864
	ds_read_b128 v[154:157], v162 offset:37888
	ds_read_b128 v[164:167], v162 offset:38912
	ds_read_b128 v[168:171], v162 offset:39936
	global_load_lds_dwordx4 v[180:181], off
	s_waitcnt vmcnt(7)
	s_waitcnt lgkmcnt(0)
	s_barrier
	s_setprio 1
	s_waitcnt lgkmcnt(0)
	v_mfma_f32_16x16x32_bf16 v[94:97], v[98:101], v[134:137], v[94:97]
	v_mfma_f32_16x16x32_bf16 v[90:93], v[106:109], v[134:137], v[90:93]
	v_mfma_f32_16x16x32_bf16 v[78:81], v[98:101], v[142:145], v[78:81]
	v_mfma_f32_16x16x32_bf16 v[74:77], v[106:109], v[142:145], v[74:77]
	v_mfma_f32_16x16x32_bf16 v[62:65], v[98:101], v[150:153], v[62:65]
	v_mfma_f32_16x16x32_bf16 v[58:61], v[106:109], v[150:153], v[58:61]
	v_mfma_f32_16x16x32_bf16 v[46:49], v[98:101], v[164:167], v[46:49]
	v_mfma_f32_16x16x32_bf16 v[42:45], v[106:109], v[164:167], v[42:45]
	v_mfma_f32_16x16x32_bf16 v[94:97], v[102:105], v[138:141], v[94:97]
	v_mfma_f32_16x16x32_bf16 v[90:93], v[110:113], v[138:141], v[90:93]
	v_mfma_f32_16x16x32_bf16 v[78:81], v[102:105], v[146:149], v[78:81]
	v_mfma_f32_16x16x32_bf16 v[74:77], v[110:113], v[146:149], v[74:77]
	v_mfma_f32_16x16x32_bf16 v[62:65], v[102:105], v[154:157], v[62:65]
	v_mfma_f32_16x16x32_bf16 v[58:61], v[110:113], v[154:157], v[58:61]
	v_mfma_f32_16x16x32_bf16 v[46:49], v[102:105], v[168:171], v[46:49]
	v_mfma_f32_16x16x32_bf16 v[42:45], v[110:113], v[168:171], v[42:45]
	s_setprio 0
	s_setprio 1
	v_mfma_f32_16x16x32_bf16 v[86:89], v[114:117], v[134:137], v[86:89]
	v_mfma_f32_16x16x32_bf16 v[82:85], v[122:125], v[134:137], v[82:85]
	v_mfma_f32_16x16x32_bf16 v[70:73], v[114:117], v[142:145], v[70:73]
	v_mfma_f32_16x16x32_bf16 v[66:69], v[122:125], v[142:145], v[66:69]
	v_mfma_f32_16x16x32_bf16 v[54:57], v[114:117], v[150:153], v[54:57]
	v_mfma_f32_16x16x32_bf16 v[50:53], v[122:125], v[150:153], v[50:53]
	v_mfma_f32_16x16x32_bf16 v[38:41], v[114:117], v[164:167], v[38:41]
	v_mfma_f32_16x16x32_bf16 v[34:37], v[122:125], v[164:167], v[34:37]
	v_mfma_f32_16x16x32_bf16 v[86:89], v[118:121], v[138:141], v[86:89]
	v_mfma_f32_16x16x32_bf16 v[82:85], v[126:129], v[138:141], v[82:85]
	v_mfma_f32_16x16x32_bf16 v[70:73], v[118:121], v[146:149], v[70:73]
	v_mfma_f32_16x16x32_bf16 v[66:69], v[126:129], v[146:149], v[66:69]
	v_mfma_f32_16x16x32_bf16 v[54:57], v[118:121], v[154:157], v[54:57]
	v_mfma_f32_16x16x32_bf16 v[50:53], v[126:129], v[154:157], v[50:53]
	v_mfma_f32_16x16x32_bf16 v[38:41], v[118:121], v[168:171], v[38:41]
	v_mfma_f32_16x16x32_bf16 v[34:37], v[126:129], v[168:171], v[34:37]
	s_setprio 0
	s_barrier
	s_mov_b32 m0, s42
	v_lshl_add_u64 v[150:151], v[172:173], 0, s[44:45]
	s_add_u32 s8, s20, 0x160080
	ds_read_b128 v[134:137], v163 offset:49152
	ds_read_b128 v[138:141], v163 offset:50176
	ds_read_b128 v[142:145], v163 offset:51200
	ds_read_b128 v[146:149], v163 offset:52224
	global_load_lds_dwordx4 v[150:151], off
	v_lshl_add_u64 v[150:151], v[174:175], 0, s[44:45]
	s_mov_b32 m0, s43
	s_addc_u32 s9, s21, 0
	global_load_lds_dwordx4 v[150:151], off
	v_lshl_add_u64 v[150:151], s[8:9], 0, v[0:1]
	s_mov_b32 m0, s52
	s_nop 0
	global_load_lds_dwordx4 v[150:151], off
	v_lshl_add_u64 v[150:151], s[8:9], 0, v[130:131]
	s_mov_b32 m0, s53
	s_nop 0
	global_load_lds_dwordx4 v[150:151], off
	s_waitcnt vmcnt(5)
	s_waitcnt lgkmcnt(0)
	s_barrier
	s_setprio 1
	s_waitcnt lgkmcnt(0)
	v_mfma_f32_16x16x32_bf16 v[30:33], v[98:101], v[134:137], v[30:33]
	v_mfma_f32_16x16x32_bf16 v[26:29], v[106:109], v[134:137], v[26:29]
	v_mfma_f32_16x16x32_bf16 v[14:17], v[98:101], v[142:145], v[14:17]
	v_lshl_add_u64 v[150:151], v[176:177], 0, s[44:45]
	s_mov_b32 m0, s49
	s_nop 0
	global_load_lds_dwordx4 v[150:151], off
	v_mfma_f32_16x16x32_bf16 v[10:13], v[106:109], v[142:145], v[10:13]
	v_mfma_f32_16x16x32_bf16 v[30:33], v[102:105], v[138:141], v[30:33]
	v_mfma_f32_16x16x32_bf16 v[26:29], v[110:113], v[138:141], v[26:29]
	v_mfma_f32_16x16x32_bf16 v[14:17], v[102:105], v[146:149], v[14:17]
	v_mfma_f32_16x16x32_bf16 v[10:13], v[110:113], v[146:149], v[10:13]
	s_setprio 0
	s_setprio 1
	v_mfma_f32_16x16x32_bf16 v[22:25], v[114:117], v[134:137], v[22:25]
	v_mfma_f32_16x16x32_bf16 v[18:21], v[122:125], v[134:137], v[18:21]
	v_mfma_f32_16x16x32_bf16 v[6:9], v[114:117], v[142:145], v[6:9]
	v_lshl_add_u64 v[150:151], v[178:179], 0, s[44:45]
	s_mov_b32 m0, s50
	s_nop 0
	global_load_lds_dwordx4 v[150:151], off
	v_mfma_f32_16x16x32_bf16 v[2:5], v[122:125], v[142:145], v[2:5]
	v_mfma_f32_16x16x32_bf16 v[22:25], v[118:121], v[138:141], v[22:25]
	v_mfma_f32_16x16x32_bf16 v[18:21], v[126:129], v[138:141], v[18:21]
	v_mfma_f32_16x16x32_bf16 v[6:9], v[118:121], v[146:149], v[6:9]
	v_mfma_f32_16x16x32_bf16 v[2:5], v[126:129], v[146:149], v[2:5]
	s_setprio 0
	s_barrier
	s_add_i32 s61, s61, 2
	s_add_u32 s0, s0, 0x100
	s_addc_u32 s60, s60, 0
	s_cmpk_gt_u32 s61, 0x55
	s_mov_b64 s[8:9], s[4:5]
	s_cbranch_scc0 .LBB0_1793
	s_and_b64 vcc, exec, s[14:15]
	s_cbranch_vccz .LBB0_1796
	s_barrier
